# sample S5 item: 16 per-token wave reductions merged into one transposed DPP reduction, skip-term u word loaded per lane; on top of pass 1 + pass 2 rewrites
# speedup vs baseline: 1.0334x; 1.0115x over previous
.LBB0_1069:
	s_or_b64 exec, exec, s[0:1]
	s_add_i32 s0, 0, 0x20170
	v_mov_b32_e32 v1, s0
	s_waitcnt lgkmcnt(0)
	s_barrier
	ds_read_b32 v1, v1
	s_movk_i32 s0, 0x1ff
	s_mov_b32 s53, 0
	s_waitcnt lgkmcnt(0)
	v_cmp_lt_u32_e32 vcc, s0, v1
	v_readfirstlane_b32 s52, v1
	s_cbranch_vccnz .LBB0_1084
	s_add_u32 s54, s72, 0xb01000
	s_addc_u32 s55, s73, 0
	s_add_u32 s56, s72, 0xb15000
	s_addc_u32 s57, s73, 0
	v_readlane_b32 s3, v252, 56
	v_ashrrev_i32_e32 v19, 31, v18
	s_bitcmp1_b32 s3, 2
	s_cselect_b64 s[58:59], -1, 0
	s_add_u32 s3, s72, 0xc300010
	v_lshl_add_u64 v[2:3], v[18:19], 1, s[72:73]
	s_mov_b64 s[4:5], 0xe500000
	v_and_b32_e32 v1, 15, v18
	v_cmp_gt_i32_e64 s[0:1], 16, v18
	v_cmp_eq_u32_e64 s[38:39], 15, v18
	v_and_b32_e32 v49, 8, v18
	v_cmp_ne_u32_e64 s[6:7], 0, v49
	v_and_b32_e32 v49, 4, v18
	v_cmp_ne_u32_e64 s[8:9], 0, v49
	v_and_b32_e32 v49, 2, v18
	v_cmp_ne_u32_e64 s[10:11], 0, v49
	v_and_b32_e32 v49, 1, v18
	v_cmp_ne_u32_e64 s[12:13], 0, v49
	v_and_b32_e32 v106, 15, v18
	v_lshlrev_b32_e32 v106, 1, v106
	v_cmp_eq_u32_e64 s[14:15], 10, v18
	v_cmp_eq_u32_e64 s[16:17], 9, v18
	v_cmp_eq_u32_e64 s[18:19], 8, v18
	v_cmp_eq_u32_e64 s[20:21], 7, v18
	v_cmp_eq_u32_e64 s[22:23], 6, v18
	v_cmp_eq_u32_e64 s[24:25], 5, v18
	v_cmp_eq_u32_e64 s[26:27], 4, v18
	v_cmp_eq_u32_e64 s[28:29], 3, v18
	v_cmp_eq_u32_e64 s[30:31], 2, v18
	s_mov_b32 s2, 1
	v_cmp_eq_u32_e64 s[34:35], 1, v18
	v_cmp_eq_u32_e64 s[36:37], 0, v18
	s_addc_u32 s33, s73, 0
	v_lshl_add_u64 v[20:21], v[2:3], 0, s[4:5]
	v_mov_b32_e32 v47, 0
	s_movk_i32 s62, 0x200
	s_branch .LBB0_1072

.LBB0_1078:
	s_add_u32 s60, s5, s44
	s_addc_u32 s61, s52, s45
	global_load_ushort v108, v106, s[60:61] offset:-16
	global_load_dwordx4 v[98:101], v47, s[60:61] offset:-16
	global_load_dwordx4 v[102:105], v47, s[60:61]
	s_waitcnt vmcnt(1)
	v_lshlrev_b32_e32 v46, 16, v98
	v_and_b32_e32 v48, 0xffff0000, v98
	v_lshlrev_b32_e32 v50, 16, v99
	v_and_b32_e32 v52, 0xffff0000, v99
	v_pk_fma_f32 v[98:99], v[2:3], v[46:47], 0 op_sel_hi:[1,0,0]
	v_lshlrev_b32_e32 v54, 16, v100
	v_pk_fma_f32 v[98:99], v[42:43], v[48:49], v[98:99] op_sel_hi:[1,0,1]
	v_and_b32_e32 v56, 0xffff0000, v100
	v_pk_fma_f32 v[98:99], v[4:5], v[50:51], v[98:99] op_sel_hi:[1,0,1]
	v_lshlrev_b32_e32 v58, 16, v101
	v_pk_fma_f32 v[98:99], v[40:41], v[52:53], v[98:99] op_sel_hi:[1,0,1]
	v_and_b32_e32 v60, 0xffff0000, v101
	v_pk_fma_f32 v[98:99], v[6:7], v[54:55], v[98:99] op_sel_hi:[1,0,1]
	s_waitcnt vmcnt(0)
	v_lshlrev_b32_e32 v62, 16, v102
	v_pk_fma_f32 v[98:99], v[38:39], v[56:57], v[98:99] op_sel_hi:[1,0,1]
	v_and_b32_e32 v64, 0xffff0000, v102
	v_pk_fma_f32 v[98:99], v[8:9], v[58:59], v[98:99] op_sel_hi:[1,0,1]
	v_lshlrev_b32_e32 v66, 16, v103
	v_pk_fma_f32 v[98:99], v[36:37], v[60:61], v[98:99] op_sel_hi:[1,0,1]
	v_and_b32_e32 v68, 0xffff0000, v103
	v_pk_fma_f32 v[98:99], v[10:11], v[62:63], v[98:99] op_sel_hi:[1,0,1]
	v_lshlrev_b32_e32 v70, 16, v104
	v_pk_fma_f32 v[98:99], v[34:35], v[64:65], v[98:99] op_sel_hi:[1,0,1]
	v_and_b32_e32 v72, 0xffff0000, v104
	v_pk_fma_f32 v[98:99], v[12:13], v[66:67], v[98:99] op_sel_hi:[1,0,1]
	v_lshlrev_b32_e32 v74, 16, v105
	v_pk_fma_f32 v[98:99], v[32:33], v[68:69], v[98:99] op_sel_hi:[1,0,1]
	v_and_b32_e32 v76, 0xffff0000, v105
	v_pk_fma_f32 v[98:99], v[14:15], v[70:71], v[98:99] op_sel_hi:[1,0,1]
	s_nop 0
	v_pk_fma_f32 v[98:99], v[30:31], v[72:73], v[98:99] op_sel_hi:[1,0,1]
	s_nop 0
	v_pk_fma_f32 v[98:99], v[16:17], v[74:75], v[98:99] op_sel_hi:[1,0,1]
	s_nop 0
	v_pk_fma_f32 v[98:99], v[28:29], v[76:77], v[98:99] op_sel_hi:[1,0,1]
	s_nop 0
	v_pk_fma_f32 v[98:99], v[26:27], v[22:23], v[98:99] op_sel:[0,1,0] op_sel_hi:[1,0,1]
	s_nop 0
	v_pk_fma_f32 v[22:23], v[24:25], v[22:23], v[98:99]
	s_nop 0
	v_mul_f32_e32 v97, v67, v22
	v_mul_f32_e32 v98, v69, v22
	v_mul_f32_e32 v99, v71, v22
	v_mul_f32_e32 v100, v73, v22
	v_mul_f32_e32 v101, v75, v22
	v_mul_f32_e32 v102, v77, v22
	v_mul_f32_e32 v109, v78, v22
	v_mul_f32_e32 v111, v79, v22
	v_mul_f32_e32 v113, v88, v22
	v_mul_f32_e32 v115, v89, v22
	v_mul_f32_e32 v117, v90, v22
	v_mul_f32_e32 v119, v91, v22
	v_mul_f32_e32 v121, v92, v22
	v_mul_f32_e32 v123, v93, v22
	v_mul_f32_e32 v125, v94, v22
	v_mul_f32_e32 v127, v95, v22
	v_fma_f32 v97, v51, v23, -v97
	v_fma_f32 v98, v53, v23, -v98
	v_fma_f32 v99, v55, v23, -v99
	v_fma_f32 v100, v57, v23, -v100
	v_fma_f32 v101, v59, v23, -v101
	v_fma_f32 v102, v61, v23, -v102
	v_fma_f32 v109, v63, v23, -v109
	v_fma_f32 v111, v65, v23, -v111
	v_fma_f32 v113, v80, v23, -v113
	v_fma_f32 v115, v81, v23, -v115
	v_fma_f32 v117, v82, v23, -v117
	v_fma_f32 v119, v83, v23, -v119
	v_fma_f32 v121, v84, v23, -v121
	v_fma_f32 v123, v85, v23, -v123
	v_fma_f32 v125, v86, v23, -v125
	v_fma_f32 v127, v87, v23, -v127
	v_add_f32_dpp v97, v97, v97 row_ror:8 row_mask:0xf bank_mask:0xf bound_ctrl:1
	v_add_f32_dpp v98, v98, v98 row_ror:8 row_mask:0xf bank_mask:0xf bound_ctrl:1
	v_add_f32_dpp v99, v99, v99 row_ror:8 row_mask:0xf bank_mask:0xf bound_ctrl:1
	v_add_f32_dpp v100, v100, v100 row_ror:8 row_mask:0xf bank_mask:0xf bound_ctrl:1
	v_add_f32_dpp v101, v101, v101 row_ror:8 row_mask:0xf bank_mask:0xf bound_ctrl:1
	v_add_f32_dpp v102, v102, v102 row_ror:8 row_mask:0xf bank_mask:0xf bound_ctrl:1
	v_add_f32_dpp v109, v109, v109 row_ror:8 row_mask:0xf bank_mask:0xf bound_ctrl:1
	v_add_f32_dpp v111, v111, v111 row_ror:8 row_mask:0xf bank_mask:0xf bound_ctrl:1
	v_add_f32_dpp v113, v113, v113 row_ror:8 row_mask:0xf bank_mask:0xf bound_ctrl:1
	v_add_f32_dpp v115, v115, v115 row_ror:8 row_mask:0xf bank_mask:0xf bound_ctrl:1
	v_add_f32_dpp v117, v117, v117 row_ror:8 row_mask:0xf bank_mask:0xf bound_ctrl:1
	v_add_f32_dpp v119, v119, v119 row_ror:8 row_mask:0xf bank_mask:0xf bound_ctrl:1
	v_add_f32_dpp v121, v121, v121 row_ror:8 row_mask:0xf bank_mask:0xf bound_ctrl:1
	v_add_f32_dpp v123, v123, v123 row_ror:8 row_mask:0xf bank_mask:0xf bound_ctrl:1
	v_add_f32_dpp v125, v125, v125 row_ror:8 row_mask:0xf bank_mask:0xf bound_ctrl:1
	v_add_f32_dpp v127, v127, v127 row_ror:8 row_mask:0xf bank_mask:0xf bound_ctrl:1
	v_cndmask_b32_e64 v97, v97, v113, s[6:7]
	v_cndmask_b32_e64 v98, v98, v115, s[6:7]
	v_cndmask_b32_e64 v99, v99, v117, s[6:7]
	v_cndmask_b32_e64 v100, v100, v119, s[6:7]
	v_cndmask_b32_e64 v101, v101, v121, s[6:7]
	v_cndmask_b32_e64 v102, v102, v123, s[6:7]
	v_cndmask_b32_e64 v109, v109, v125, s[6:7]
	v_cndmask_b32_e64 v111, v111, v127, s[6:7]
	v_add_f32_dpp v97, v97, v97 row_half_mirror row_mask:0xf bank_mask:0xf bound_ctrl:1
	v_add_f32_dpp v98, v98, v98 row_half_mirror row_mask:0xf bank_mask:0xf bound_ctrl:1
	v_add_f32_dpp v99, v99, v99 row_half_mirror row_mask:0xf bank_mask:0xf bound_ctrl:1
	v_add_f32_dpp v100, v100, v100 row_half_mirror row_mask:0xf bank_mask:0xf bound_ctrl:1
	v_add_f32_dpp v101, v101, v101 row_half_mirror row_mask:0xf bank_mask:0xf bound_ctrl:1
	v_add_f32_dpp v102, v102, v102 row_half_mirror row_mask:0xf bank_mask:0xf bound_ctrl:1
	v_add_f32_dpp v109, v109, v109 row_half_mirror row_mask:0xf bank_mask:0xf bound_ctrl:1
	v_add_f32_dpp v111, v111, v111 row_half_mirror row_mask:0xf bank_mask:0xf bound_ctrl:1
	v_cndmask_b32_e64 v97, v97, v101, s[8:9]
	v_cndmask_b32_e64 v98, v98, v102, s[8:9]
	v_cndmask_b32_e64 v99, v99, v109, s[8:9]
	v_cndmask_b32_e64 v100, v100, v111, s[8:9]
	v_add_f32_dpp v97, v97, v97 quad_perm:[3,2,1,0] row_mask:0xf bank_mask:0xf bound_ctrl:1
	v_add_f32_dpp v98, v98, v98 quad_perm:[3,2,1,0] row_mask:0xf bank_mask:0xf bound_ctrl:1
	v_add_f32_dpp v99, v99, v99 quad_perm:[3,2,1,0] row_mask:0xf bank_mask:0xf bound_ctrl:1
	v_add_f32_dpp v100, v100, v100 quad_perm:[3,2,1,0] row_mask:0xf bank_mask:0xf bound_ctrl:1
	v_cndmask_b32_e64 v97, v97, v99, s[10:11]
	v_cndmask_b32_e64 v98, v98, v100, s[10:11]
	s_nop 1
	v_add_f32_dpp v97, v97, v97 quad_perm:[1,0,3,2] row_mask:0xf bank_mask:0xf bound_ctrl:1
	v_add_f32_dpp v98, v98, v98 quad_perm:[1,0,3,2] row_mask:0xf bank_mask:0xf bound_ctrl:1
	v_cndmask_b32_e64 v97, v97, v98, s[12:13]
	v_mov_b32_e32 v110, v97
	s_nop 1
	v_permlane16_swap_b32_e32 v97, v110
	v_add_f32_e32 v97, v97, v110
	v_mov_b32_e32 v110, v97
	s_nop 1
	v_permlane32_swap_b32_e32 v97, v110
	s_and_saveexec_b64 s[60:61], s[0:1]
	s_cbranch_execz .LBB0_1077
	v_add_f32_e32 v97, v97, v110
	v_lshlrev_b32_e32 v46, 16, v108
	v_fma_f32 v48, v96, v46, v97
	v_mul_f32_e32 v46, 0x3d372713, v48
	v_mul_f32_e32 v46, v48, v46
	v_fma_f32 v46, v48, v46, v48
	v_mul_f32_e32 v46, 0xbfcc422a, v46
	v_mul_f32_e32 v46, 0x3fb8aa3b, v46
	v_exp_f32_e32 v46, v46
	v_lshl_add_u64 v[98:99], v[44:45], 0, s[44:45]
	v_add_f32_e32 v46, 1.0, v46
	v_rcp_f32_e32 v46, v46
	s_nop 0
	v_mul_f32_e32 v46, v48, v46
	v_cvt_pk_bf16_f32 v46, v46, v46
	global_store_short v[98:99], v46, off
	s_branch .LBB0_1077
